# GQA attention loop: softmax VALU (exp/sum/cvt/permlane) redistributed evenly into QK^T MFMA gaps; conditional vmcnt drain replaces compiler ladder
# speedup vs baseline: 1.0137x; 1.0137x over previous
; #define SBAR() __builtin_amdgcn_sched_barrier(0)
; #define SLOAD(i, k0) do { sr_[i].vs0 = *reinterpret_cast<const bf16x8*>(vptr + (size_t)((k0) + sr) * vstr); \
;     sr_[i].vs1 = *reinterpret_cast<const bf16x8*>(vptr + (size_t)((k0) + 32 + sr) * vstr); \
;     sr_[i].ks0 = *reinterpret_cast<const bf16x8*>(kptr + (size_t)((k0) + sr) * kstr); \
;     sr_[i].ks1 = *reinterpret_cast<const bf16x8*>(kptr + (size_t)((k0) + 32 + sr) * kstr); } while (0)
; __device__ __forceinline__ void finishSM(f32x16& p0, f32x16& p1, float alpha, float& l_reg, bf16x8& pa0, bf16x8& pa1, bf16x8& pa2, bf16x8& pa3) {
; #pragma unroll
;   for (int r = 0; r < 16; ++r) p1[r] = __builtin_amdgcn_exp2f(p1[r]);
;   float ps = 0;
; #pragma unroll
;   for (int r = 0; r < 16; ++r) ps += p0[r];
; #pragma unroll
;   for (int r = 0; r < 16; ++r) ps += p1[r];
;   { auto rr = __builtin_amdgcn_permlane32_swap(__float_as_uint(ps), __float_as_uint(ps), false, false);
;     ps = __uint_as_float(rr[0]) + __uint_as_float(rr[1]); }
;   l_reg = l_reg * alpha + ps;
;     ...
;   PK4(p0, 0, pa0); PK4(p0, 8, pa1); PK4(p1, 0, pa2); PK4(p1, 8, pa3);
; template <int NDQ, int NDV> ...
;     ...
;     SBAR(); qkt<NDQ>(pB0, pB1, K_lds + SHM_K, qr, r32, hi);
;     finishSM(pA0, pA1, alA, l_reg, pa0, pa1, pa2, pa3); SBAR();
;     SLOAD(SO, (j + 2) * 64); SBAR();
.LBB0_2123:
	ds_read_b128 v[64:67], v199 offset:49152
	ds_read_b128 v[68:71], v199 offset:57344
	ds_read_b128 v[216:219], v200 offset:49152
	ds_read_b128 v[220:223], v200 offset:57344
	v_add_f32_e32 v161, 0, v175
	v_add_f32_e32 v161, v214, v161
	s_waitcnt lgkmcnt(3)
	v_mfma_f32_32x32x16_bf16 v[80:95], v[64:67], v[124:127], 0
	v_add_f32_e32 v161, v173, v161
	v_add_f32_e32 v161, v211, v161
	v_add_f32_e32 v161, v172, v161
	v_add_f32_e32 v161, v174, v161
	v_add_f32_e32 v161, v170, v161
	v_add_f32_e32 v161, v171, v161
	s_waitcnt lgkmcnt(2)
	v_mfma_f32_32x32x16_bf16 v[64:79], v[68:71], v[124:127], 0
	v_add_f32_e32 v161, v167, v161
	v_add_f32_e32 v161, v169, v161
	v_add_f32_e32 v161, v166, v161
	v_add_f32_e32 v161, v168, v161
	v_exp_f32_e32 v154, v154
	s_waitcnt lgkmcnt(1)
	v_mfma_f32_32x32x16_bf16 v[80:95], v[216:219], v[120:123], v[80:95]
	v_add_f32_e32 v161, v163, v161
	v_exp_f32_e32 v155, v155
	v_add_f32_e32 v161, v165, v161
	v_exp_f32_e32 v152, v152
	s_waitcnt lgkmcnt(0)
	v_mfma_f32_32x32x16_bf16 v[64:79], v[220:223], v[120:123], v[64:79]
	ds_read_b128 v[216:219], v201 offset:49152
	ds_read_b128 v[220:223], v201 offset:57344
	v_add_f32_e32 v161, v162, v161
	v_exp_f32_e32 v153, v153
	v_add_f32_e32 v161, v164, v161
	v_exp_f32_e32 v148, v148
	s_waitcnt lgkmcnt(1)
	v_mfma_f32_32x32x16_bf16 v[80:95], v[216:219], v[116:119], v[80:95]
	v_add_f32_e32 v161, v154, v161
	v_exp_f32_e32 v149, v149
	v_add_f32_e32 v161, v155, v161
	v_exp_f32_e32 v146, v146
	s_waitcnt lgkmcnt(0)
	v_mfma_f32_32x32x16_bf16 v[64:79], v[220:223], v[116:119], v[64:79]
	ds_read_b128 v[216:219], v202 offset:49152
	ds_read_b128 v[220:223], v202 offset:57344
	v_add_f32_e32 v161, v152, v161
	v_exp_f32_e32 v147, v147
	v_add_f32_e32 v161, v153, v161
	v_exp_f32_e32 v144, v144
	s_waitcnt lgkmcnt(1)
	v_mfma_f32_32x32x16_bf16 v[80:95], v[216:219], v[112:115], v[80:95]
	v_add_f32_e32 v161, v148, v161
	v_exp_f32_e32 v145, v145
	v_add_f32_e32 v161, v149, v161
	v_exp_f32_e32 v158, v158
	s_waitcnt lgkmcnt(0)
	v_mfma_f32_32x32x16_bf16 v[64:79], v[220:223], v[112:115], v[64:79]
	ds_read_b128 v[216:219], v203 offset:49152
	ds_read_b128 v[220:223], v203 offset:57344
	v_add_f32_e32 v161, v146, v161
	v_exp_f32_e32 v159, v159
	v_add_f32_e32 v161, v147, v161
	v_exp_f32_e32 v156, v156
	s_waitcnt lgkmcnt(1)
	v_mfma_f32_32x32x16_bf16 v[80:95], v[216:219], v[108:111], v[80:95]
	v_add_f32_e32 v161, v144, v161
	v_exp_f32_e32 v157, v157
	v_add_f32_e32 v161, v145, v161
	v_exp_f32_e32 v150, v150
	s_waitcnt lgkmcnt(0)
	v_mfma_f32_32x32x16_bf16 v[64:79], v[220:223], v[108:111], v[64:79]
	ds_read_b128 v[216:219], v204 offset:49152
	ds_read_b128 v[220:223], v204 offset:57344
	v_add_f32_e32 v161, v158, v161
	v_exp_f32_e32 v151, v151
	v_add_f32_e32 v161, v159, v161
	v_add_f32_e32 v161, v156, v161
	v_add_f32_e32 v161, v157, v161
	s_waitcnt lgkmcnt(1)
	v_mfma_f32_32x32x16_bf16 v[80:95], v[216:219], v[104:107], v[80:95]
	v_add_f32_e32 v161, v150, v161
	v_add_f32_e32 v208, v151, v161
	v_mov_b32_e32 v209, v208
	v_cvt_pk_bf16_f32 v210, v175, v214
	v_cvt_pk_bf16_f32 v211, v173, v211
	v_cvt_pk_bf16_f32 v212, v172, v174
	s_waitcnt lgkmcnt(0)
	v_mfma_f32_32x32x16_bf16 v[64:79], v[220:223], v[104:107], v[64:79]
	ds_read_b128 v[216:219], v205 offset:49152
	ds_read_b128 v[220:223], v205 offset:57344
	v_permlane32_swap_b32_e32 v208, v209
	v_cvt_pk_bf16_f32 v213, v170, v171
	v_cvt_pk_bf16_f32 v170, v167, v169
	v_cvt_pk_bf16_f32 v171, v166, v168
	v_permlane32_swap_b32_e32 v210, v212
	v_cvt_pk_bf16_f32 v172, v163, v165
	s_waitcnt lgkmcnt(1)
	v_mfma_f32_32x32x16_bf16 v[80:95], v[216:219], v[100:103], v[80:95]
	v_cvt_pk_bf16_f32 v173, v162, v164
	v_cvt_pk_bf16_f32 v162, v154, v155
	v_cvt_pk_bf16_f32 v163, v152, v153
	v_cvt_pk_bf16_f32 v164, v148, v149
	v_cvt_pk_bf16_f32 v165, v146, v147
	v_cvt_pk_bf16_f32 v166, v144, v145
	s_waitcnt lgkmcnt(0)
	v_mfma_f32_32x32x16_bf16 v[64:79], v[220:223], v[100:103], v[64:79]
	ds_read_b128 v[216:219], v206 offset:49152
	ds_read_b128 v[220:223], v206 offset:57344
	v_cvt_pk_bf16_f32 v167, v158, v159
	v_cvt_pk_bf16_f32 v168, v156, v157
	v_cvt_pk_bf16_f32 v169, v150, v151
	v_permlane32_swap_b32_e32 v211, v213
	v_permlane32_swap_b32_e32 v170, v172
	v_permlane32_swap_b32_e32 v171, v173
	s_waitcnt lgkmcnt(1)
	v_mfma_f32_32x32x16_bf16 v[80:95], v[216:219], v[96:99], v[80:95]
	v_permlane32_swap_b32_e32 v162, v164
	v_permlane32_swap_b32_e32 v163, v165
	v_permlane32_swap_b32_e32 v166, v168
	v_permlane32_swap_b32_e32 v167, v169
	s_waitcnt lgkmcnt(0)
	v_mfma_f32_32x32x16_bf16 v[64:79], v[220:223], v[96:99], v[64:79]
	v_add_co_u32_e32 v148, vcc, s50, v184
	s_nop 1
	v_addc_co_u32_e32 v149, vcc, -1, v185, vcc
	v_add_co_u32_e32 v152, vcc, s51, v184
	s_nop 1
	v_addc_co_u32_e32 v153, vcc, -1, v185, vcc
	global_load_dwordx4 v[144:147], v[148:149], off
	s_nop 0
	global_load_dwordx4 v[148:151], v[148:149], off offset:-512
	s_nop 0
	global_load_dwordx4 v[156:159], v[152:153], off
	s_nop 0
	global_load_dwordx4 v[152:155], v[152:153], off offset:-512
	ds_read_b64_tr_b16 v[214:215], v194 offset:0
	ds_read_b64_tr_b16 v[216:217], v194 offset:0x800
	ds_read_b64_tr_b16 v[218:219], v194 offset:0x1000
	ds_read_b64_tr_b16 v[220:221], v194 offset:0x1800
	ds_read_b64_tr_b16 v[222:223], v194 offset:0x2000
	ds_read_b64_tr_b16 v[224:225], v194 offset:0x2800
	ds_read_b64_tr_b16 v[226:227], v194 offset:0x3000
	ds_read_b64_tr_b16 v[228:229], v194 offset:0x3800
	s_waitcnt lgkmcnt(0)
; #define SBAR() __builtin_amdgcn_sched_barrier(0)
; #define SWAIT() asm volatile("s_waitcnt vmcnt(4)" ::: "memory")
; __device__ __forceinline__ void partialSM(f32x16& p0, f32x16& p1, float& m_reg, float& mn, float& alpha, float C, float thr) {
;   float pmax = p0[0];
; #pragma unroll
;   for (int r = 1; r < 16; ++r) pmax = fmaxf(pmax, p0[r]);
; #pragma unroll
;   for (int r = 0; r < 16; ++r) pmax = fmaxf(pmax, p1[r]);
;   { auto rr = __builtin_amdgcn_permlane32_swap(__float_as_uint(pmax), __float_as_uint(pmax), false, false);
;     pmax = fmaxf(__uint_as_float(rr[0]), __uint_as_float(rr[1])); }
;   if (__builtin_expect(__all(pmax - m_reg <= thr), 1)) { mn = m_reg; alpha = 1.f; }
;   else { mn = fmaxf(m_reg, pmax); alpha = __builtin_amdgcn_exp2f((m_reg - mn) * C); m_reg = mn; }
; template <int D0> __device__ __forceinline__ void pv_one(f32x16& od, int vb, bf16x8 pa0, bf16x8 pa1, bf16x8 pa2, bf16x8 pa3) {
;   const s16x4 l0 = tr_read<v_rd_off(D0, 0, 0)>(vb), h0 = tr_read<v_rd_off(D0, 0, 1)>(vb), l1 = tr_read<v_rd_off(D0, 1, 0)>(vb), h1 = tr_read<v_rd_off(D0, 1, 1)>(vb);
;   const s16x4 l2 = tr_read<v_rd_off(D0, 2, 0)>(vb), h2 = tr_read<v_rd_off(D0, 2, 1)>(vb), l3 = tr_read<v_rd_off(D0, 3, 0)>(vb), h3 = tr_read<v_rd_off(D0, 3, 1)>(vb);
;   asm volatile("s_waitcnt lgkmcnt(0)" ::: "memory"); SBAR();
;     ...
;   od = __builtin_amdgcn_mfma_f32_32x32x16_bf16(pa0, PK(l0, h0), od, 0, 0, 0);
;   od = __builtin_amdgcn_mfma_f32_32x32x16_bf16(pa1, PK(l1, h1), od, 0, 0, 0);
;   od = __builtin_amdgcn_mfma_f32_32x32x16_bf16(pa2, PK(l2, h2), od, 0, 0, 0);
;   od = __builtin_amdgcn_mfma_f32_32x32x16_bf16(pa3, PK(l3, h3), od, 0, 0, 0);
;     ...
; }
; template <int NDV>
; __device__ __forceinline__ void pv_d0(f32x16* o, int vb, bf16x8 pa0, bf16x8 pa1, bf16x8 pa2, bf16x8 pa3) {
;   pv_one<0>(o[0], vb, pa0, pa1, pa2, pa3); pv_one<1>(o[1], vb, pa0, pa1, pa2, pa3);
;   if constexpr (NDV == 4) { pv_one<2>(o[2], vb, pa0, pa1, pa2, pa3); pv_one<3>(o[3], vb, pa0, pa1, pa2, pa3); }
; }
; template <int NDQ, int NDV> ...
;     ...
;     pv_d0<NDV>(o, vb0, pa0, pa1, pa2, pa3); partialSM(pB0, pB1, m_reg, mnB, alB, Cs, thr);
;     __syncthreads(); SWAIT(); SWRITE(0, SE);
;     RESC(alB); __syncthreads();
	s_nop 0
	v_mfma_f32_32x32x16_bf16 v[0:15], v[210:213], v[214:217], v[0:15]
	ds_read_b64_tr_b16 v[214:215], v194 offset:0x200
	ds_read_b64_tr_b16 v[216:217], v194 offset:0xa00
	v_mfma_f32_32x32x16_bf16 v[0:15], v[170:173], v[218:221], v[0:15]
	ds_read_b64_tr_b16 v[218:219], v194 offset:0x1200
	ds_read_b64_tr_b16 v[220:221], v194 offset:0x1a00
	v_mfma_f32_32x32x16_bf16 v[0:15], v[162:165], v[222:225], v[0:15]
	ds_read_b64_tr_b16 v[222:223], v194 offset:0x2200
	ds_read_b64_tr_b16 v[224:225], v194 offset:0x2a00
	ds_read_b64_tr_b16 v[230:231], v194 offset:0x3200
	ds_read_b64_tr_b16 v[232:233], v194 offset:0x3a00
	s_waitcnt lgkmcnt(0)
	v_mfma_f32_32x32x16_bf16 v[0:15], v[166:169], v[226:229], v[0:15]
	v_mfma_f32_32x32x16_bf16 v[48:63], v[210:213], v[214:217], v[48:63]
	ds_read_b64_tr_b16 v[214:215], v194 offset:0x400
	ds_read_b64_tr_b16 v[216:217], v194 offset:0xc00
	v_mfma_f32_32x32x16_bf16 v[48:63], v[170:173], v[218:221], v[48:63]
	ds_read_b64_tr_b16 v[218:219], v194 offset:0x1400
	ds_read_b64_tr_b16 v[220:221], v194 offset:0x1c00
	v_mfma_f32_32x32x16_bf16 v[48:63], v[162:165], v[222:225], v[48:63]
	ds_read_b64_tr_b16 v[222:223], v194 offset:0x2400
	ds_read_b64_tr_b16 v[224:225], v194 offset:0x2c00
	ds_read_b64_tr_b16 v[226:227], v194 offset:0x3400
	ds_read_b64_tr_b16 v[228:229], v194 offset:0x3c00
	s_waitcnt lgkmcnt(0)
	v_mfma_f32_32x32x16_bf16 v[48:63], v[166:169], v[230:233], v[48:63]
	v_mfma_f32_32x32x16_bf16 v[32:47], v[210:213], v[214:217], v[32:47]
	ds_read_b64_tr_b16 v[214:215], v194 offset:0x600
	ds_read_b64_tr_b16 v[216:217], v194 offset:0xe00
	v_mfma_f32_32x32x16_bf16 v[32:47], v[170:173], v[218:221], v[32:47]
	ds_read_b64_tr_b16 v[218:219], v194 offset:0x1600
	ds_read_b64_tr_b16 v[220:221], v194 offset:0x1e00
	v_mfma_f32_32x32x16_bf16 v[32:47], v[162:165], v[222:225], v[32:47]
	ds_read_b64_tr_b16 v[222:223], v194 offset:0x2600
	ds_read_b64_tr_b16 v[224:225], v194 offset:0x2e00
	ds_read_b64_tr_b16 v[230:231], v194 offset:0x3600
	ds_read_b64_tr_b16 v[232:233], v194 offset:0x3e00
	s_waitcnt lgkmcnt(0)
	v_mfma_f32_32x32x16_bf16 v[32:47], v[166:169], v[226:229], v[32:47]
	v_mfma_f32_32x32x16_bf16 v[16:31], v[210:213], v[214:217], v[16:31]
	v_max_f32_e32 v161, v81, v81
	v_max_f32_e32 v174, v80, v80
	v_max_f32_e32 v161, v174, v161
	v_max3_f32 v161, v161, v82, v83
	v_max3_f32 v161, v161, v84, v85
	v_max3_f32 v161, v161, v86, v87
	v_max3_f32 v161, v161, v88, v89
	v_max3_f32 v161, v161, v90, v91
	v_mfma_f32_32x32x16_bf16 v[16:31], v[170:173], v[218:221], v[16:31]
	v_max3_f32 v161, v161, v92, v93
	v_max3_f32 v161, v161, v94, v95
	v_max3_f32 v161, v161, v64, v65
	v_max3_f32 v161, v161, v66, v67
	v_max3_f32 v161, v161, v68, v69
	v_max3_f32 v161, v161, v70, v71
	v_max3_f32 v161, v161, v72, v73
	v_max3_f32 v161, v161, v74, v75
	v_mfma_f32_32x32x16_bf16 v[16:31], v[162:165], v[222:225], v[16:31]
	v_max3_f32 v161, v161, v76, v77
	v_max3_f32 v161, v161, v78, v79
	v_mov_b32_e32 v170, v161
	s_nop 1
	v_permlane32_swap_b32_e32 v161, v170
	v_max_f32_e32 v162, v170, v170
	v_max_f32_e32 v161, v161, v161
	v_max_f32_e32 v161, v161, v162
	v_max_f32_e32 v163, v160, v160
	v_sub_f32_e32 v162, v161, v160
	v_max_f32_e32 v161, v163, v161
	v_mfma_f32_32x32x16_bf16 v[16:31], v[166:169], v[230:233], v[16:31]
	v_sub_f32_e32 v163, v160, v161
	v_mul_f32_e32 v163, 0x3e0293ee, v163
	v_exp_f32_e32 v163, v163
	v_cmp_ge_f32_e32 vcc, s48, v162
	s_cmp_eq_u64 vcc, exec
	s_cselect_b64 s[2:3], -1, 0
	s_barrier
	s_waitcnt vmcnt(4)
	v_cndmask_b32_e64 v210, v163, 1.0, s[2:3]
	v_cmp_gt_f32_e32 vcc, 1.0, v210
	s_waitcnt vmcnt(4)
	ds_write_b128 v197, v[128:131]
	ds_write_b128 v198, v[136:139]
	ds_write_b128 v195, v[140:143] offset:32768
	ds_write_b128 v196, v[132:135] offset:32768
	s_cbranch_vccz .LBB0_2127
	s_and_saveexec_b64 s[30:31], s[0:1]
	ds_write_b32 v191, v210 offset:128
	s_or_b64 exec, exec, s[30:31]
	s_waitcnt lgkmcnt(0)
	v_add_u32_e32 v174, v183, v176
	ds_read_b128 v[162:165], v174 offset:224
	ds_read_b128 v[166:169], v174 offset:192
	ds_read_b128 v[170:173], v174 offset:160
	ds_read_b128 v[212:215], v174 offset:128
	s_waitcnt lgkmcnt(3)
	v_pk_mul_f32 v[12:13], v[12:13], v[162:163]
	s_waitcnt lgkmcnt(2)
	v_pk_mul_f32 v[8:9], v[8:9], v[166:167]
	s_waitcnt lgkmcnt(1)
	v_pk_mul_f32 v[4:5], v[4:5], v[170:171]
	v_pk_mul_f32 v[14:15], v[14:15], v[164:165]
	v_pk_mul_f32 v[10:11], v[10:11], v[168:169]
	v_pk_mul_f32 v[6:7], v[6:7], v[172:173]
	s_waitcnt lgkmcnt(0)
	v_pk_mul_f32 v[2:3], v[2:3], v[214:215]
	v_pk_mul_f32 v[0:1], v[0:1], v[212:213]
	v_pk_mul_f32 v[60:61], v[60:61], v[162:163]
	v_pk_mul_f32 v[56:57], v[56:57], v[166:167]
	v_pk_mul_f32 v[52:53], v[52:53], v[170:171]
	v_pk_mul_f32 v[62:63], v[62:63], v[164:165]
	v_pk_mul_f32 v[58:59], v[58:59], v[168:169]
	v_pk_mul_f32 v[54:55], v[54:55], v[172:173]
	v_pk_mul_f32 v[50:51], v[50:51], v[214:215]
	v_pk_mul_f32 v[48:49], v[48:49], v[212:213]
	v_pk_mul_f32 v[44:45], v[44:45], v[162:163]
	v_pk_mul_f32 v[40:41], v[40:41], v[166:167]
	v_pk_mul_f32 v[36:37], v[36:37], v[170:171]
	v_pk_mul_f32 v[46:47], v[46:47], v[164:165]
	v_pk_mul_f32 v[42:43], v[42:43], v[168:169]
	v_pk_mul_f32 v[38:39], v[38:39], v[172:173]
	v_pk_mul_f32 v[34:35], v[34:35], v[214:215]
	v_pk_mul_f32 v[32:33], v[32:33], v[212:213]
	v_pk_mul_f32 v[28:29], v[28:29], v[162:163]
	v_pk_mul_f32 v[24:25], v[24:25], v[166:167]
	v_pk_mul_f32 v[20:21], v[20:21], v[170:171]
	v_pk_mul_f32 v[30:31], v[30:31], v[164:165]
	v_pk_mul_f32 v[26:27], v[26:27], v[168:169]
	v_pk_mul_f32 v[22:23], v[22:23], v[172:173]
	v_pk_mul_f32 v[18:19], v[18:19], v[214:215]
	v_pk_mul_f32 v[16:17], v[16:17], v[212:213]
; #define SBAR() __builtin_amdgcn_sched_barrier(0)
; #define SLOAD(i, k0) do { sr_[i].vs0 = *reinterpret_cast<const bf16x8*>(vptr + (size_t)((k0) + sr) * vstr); \
;     sr_[i].vs1 = *reinterpret_cast<const bf16x8*>(vptr + (size_t)((k0) + 32 + sr) * vstr); \
;     sr_[i].ks0 = *reinterpret_cast<const bf16x8*>(kptr + (size_t)((k0) + sr) * kstr); \
;     sr_[i].ks1 = *reinterpret_cast<const bf16x8*>(kptr + (size_t)((k0) + 32 + sr) * kstr); } while (0)
; #define RESC(a) do { if (__any((a) < 1.f)) { if (hi == 0) al_l[r32] = (a); asm volatile("s_waitcnt lgkmcnt(0)" ::: "memory"); \
;     _Pragma("unroll") for (int d = 0; d < NDV; ++d) _Pragma("unroll") for (int r = 0; r < 16; ++r) o[d][r] *= al_l[crow(r, hi)]; } } while (0)
; __device__ __forceinline__ void partialSM(f32x16& p0, f32x16& p1, float& m_reg, float& mn, float& alpha, float C, float thr) {
;     ...
;   else { mn = fmaxf(m_reg, pmax); alpha = __builtin_amdgcn_exp2f((m_reg - mn) * C); m_reg = mn; }
;   const float mnC = -mn * C;
; #pragma unroll
;   for (int r = 0; r < 16; ++r) p0[r] = fmaf(p0[r], C, mnC);
; #pragma unroll
;   for (int r = 0; r < 16; ++r) p1[r] = fmaf(p1[r], C, mnC);
; #pragma unroll
;   for (int r = 0; r < 16; ++r) p0[r] = __builtin_amdgcn_exp2f(p0[r]);
; }
; template <int NDQ, int NDV> ...
;     ...
;     RESC(alB); __syncthreads();
;     SBAR(); qkt<NDQ>(pA0, pA1, K_lds, qr, r32, hi);
;     finishSM(pB0, pB1, alB, l_reg, pa0, pa1, pa2, pa3); SBAR();
;     if (j + 3 < NT) SLOAD(SE, (j + 3) * 64); SBAR();
.LBB0_2127:
	v_cndmask_b32_e64 v211, v161, v160, s[2:3]
	v_mul_f32_e32 v212, 0xbe0293ee, v211
	v_fmamk_f32 v80, v80, 0x3e0293ee, v212
	v_fmamk_f32 v81, v81, 0x3e0293ee, v212
	v_fmamk_f32 v82, v82, 0x3e0293ee, v212
	v_fmamk_f32 v83, v83, 0x3e0293ee, v212
	v_fmamk_f32 v84, v84, 0x3e0293ee, v212
	v_fmamk_f32 v85, v85, 0x3e0293ee, v212
	v_fmamk_f32 v86, v86, 0x3e0293ee, v212
	v_fmamk_f32 v87, v87, 0x3e0293ee, v212
	v_fmamk_f32 v88, v88, 0x3e0293ee, v212
	v_fmamk_f32 v89, v89, 0x3e0293ee, v212
	v_fmamk_f32 v90, v90, 0x3e0293ee, v212
	v_fmamk_f32 v91, v91, 0x3e0293ee, v212
	v_fmamk_f32 v92, v92, 0x3e0293ee, v212
	v_fmamk_f32 v93, v93, 0x3e0293ee, v212
	v_fmamk_f32 v94, v94, 0x3e0293ee, v212
	v_fmamk_f32 v95, v95, 0x3e0293ee, v212
	v_exp_f32_e32 v160, v80
	v_exp_f32_e32 v175, v81
	v_exp_f32_e32 v161, v82
	v_exp_f32_e32 v174, v83
	v_exp_f32_e32 v162, v84
	v_exp_f32_e32 v173, v85
	v_exp_f32_e32 v163, v86
	v_exp_f32_e32 v172, v87
	v_exp_f32_e32 v164, v88
	v_exp_f32_e32 v171, v89
	v_exp_f32_e32 v165, v90
	v_exp_f32_e32 v170, v91
	v_exp_f32_e32 v166, v92
	v_exp_f32_e32 v169, v93
	v_exp_f32_e32 v167, v94
	v_exp_f32_e32 v168, v95
	v_fmamk_f32 v221, v64, 0x3e0293ee, v212
	v_fmamk_f32 v222, v65, 0x3e0293ee, v212
	v_fmamk_f32 v223, v66, 0x3e0293ee, v212
	v_fmamk_f32 v224, v67, 0x3e0293ee, v212
	v_fmamk_f32 v225, v68, 0x3e0293ee, v212
	v_fmamk_f32 v214, v69, 0x3e0293ee, v212
	v_fmamk_f32 v215, v70, 0x3e0293ee, v212
	v_fmamk_f32 v216, v71, 0x3e0293ee, v212
	v_fmamk_f32 v217, v72, 0x3e0293ee, v212
	v_fmamk_f32 v218, v73, 0x3e0293ee, v212
	v_fmamk_f32 v219, v74, 0x3e0293ee, v212
	v_fmamk_f32 v220, v75, 0x3e0293ee, v212
	v_fmamk_f32 v213, v76, 0x3e0293ee, v212
	v_fmamk_f32 v226, v77, 0x3e0293ee, v212
	v_fmamk_f32 v227, v78, 0x3e0293ee, v212
	v_fmac_f32_e32 v212, 0x3e0293ee, v79
	s_add_i32 s61, s61, 2
	s_waitcnt lgkmcnt(0)
	s_barrier
	ds_read_b128 v[64:67], v199 offset:32768
	ds_read_b128 v[68:71], v199 offset:40960
	ds_read_b128 v[228:231], v200 offset:32768
	ds_read_b128 v[232:235], v200 offset:40960
	v_exp_f32_e32 v221, v221
	v_exp_f32_e32 v222, v222
	s_waitcnt lgkmcnt(3)
	v_mfma_f32_32x32x16_bf16 v[80:95], v[64:67], v[124:127], 0
	v_exp_f32_e32 v223, v223
	v_exp_f32_e32 v224, v224
	v_exp_f32_e32 v225, v225
	s_waitcnt lgkmcnt(2)
	v_mfma_f32_32x32x16_bf16 v[64:79], v[68:71], v[124:127], 0
	v_exp_f32_e32 v214, v214
	v_exp_f32_e32 v215, v215
	v_exp_f32_e32 v216, v216
	s_waitcnt lgkmcnt(1)
	v_mfma_f32_32x32x16_bf16 v[80:95], v[228:231], v[120:123], v[80:95]
	v_exp_f32_e32 v217, v217
	v_exp_f32_e32 v218, v218
	v_exp_f32_e32 v219, v219
	s_waitcnt lgkmcnt(0)
	v_mfma_f32_32x32x16_bf16 v[64:79], v[232:235], v[120:123], v[64:79]
	ds_read_b128 v[228:231], v201 offset:32768
	ds_read_b128 v[232:235], v201 offset:40960
	v_exp_f32_e32 v220, v220
	v_exp_f32_e32 v226, v226
	v_exp_f32_e32 v227, v227
	s_waitcnt lgkmcnt(1)
	v_mfma_f32_32x32x16_bf16 v[80:95], v[228:231], v[116:119], v[80:95]
	v_exp_f32_e32 v253, v212
	v_exp_f32_e32 v252, v213
	v_add_f32_e32 v212, 0, v160
	v_add_f32_e32 v212, v175, v212
	s_waitcnt lgkmcnt(0)
	v_mfma_f32_32x32x16_bf16 v[64:79], v[232:235], v[116:119], v[64:79]
	ds_read_b128 v[228:231], v202 offset:32768
	ds_read_b128 v[232:235], v202 offset:40960
	v_add_f32_e32 v212, v161, v212
	v_add_f32_e32 v212, v174, v212
	v_add_f32_e32 v212, v162, v212
	v_add_f32_e32 v212, v173, v212
	v_add_f32_e32 v212, v163, v212
	v_add_f32_e32 v212, v172, v212
	s_waitcnt lgkmcnt(1)
	v_mfma_f32_32x32x16_bf16 v[80:95], v[228:231], v[112:115], v[80:95]
	v_add_f32_e32 v212, v164, v212
	v_add_f32_e32 v212, v171, v212
	v_add_f32_e32 v212, v165, v212
	v_add_f32_e32 v212, v170, v212
	v_add_f32_e32 v212, v166, v212
	v_add_f32_e32 v212, v169, v212
	s_waitcnt lgkmcnt(0)
	v_mfma_f32_32x32x16_bf16 v[64:79], v[232:235], v[112:115], v[64:79]
	ds_read_b128 v[228:231], v203 offset:32768
	ds_read_b128 v[232:235], v203 offset:40960
	v_add_f32_e32 v212, v167, v212
	v_add_f32_e32 v212, v168, v212
	v_add_f32_e32 v212, v221, v212
	v_add_f32_e32 v212, v222, v212
	v_add_f32_e32 v212, v223, v212
	v_add_f32_e32 v212, v224, v212
	s_waitcnt lgkmcnt(1)
	v_mfma_f32_32x32x16_bf16 v[80:95], v[228:231], v[108:111], v[80:95]
	v_add_f32_e32 v212, v225, v212
	v_add_f32_e32 v212, v214, v212
	v_add_f32_e32 v212, v215, v212
	v_add_f32_e32 v212, v216, v212
	v_add_f32_e32 v212, v217, v212
	v_add_f32_e32 v212, v218, v212
	s_waitcnt lgkmcnt(0)
	v_mfma_f32_32x32x16_bf16 v[64:79], v[232:235], v[108:111], v[64:79]
	ds_read_b128 v[228:231], v204 offset:32768
	ds_read_b128 v[232:235], v204 offset:40960
	v_add_f32_e32 v212, v219, v212
	v_add_f32_e32 v212, v220, v212
	v_add_f32_e32 v212, v252, v212
	v_add_f32_e32 v212, v226, v212
	v_add_f32_e32 v212, v227, v212
	v_add_f32_e32 v212, v253, v212
	s_waitcnt lgkmcnt(1)
	v_mfma_f32_32x32x16_bf16 v[80:95], v[228:231], v[104:107], v[80:95]
	v_mov_b32_e32 v213, v212
	v_cvt_pk_bf16_f32 v160, v160, v175
	v_cvt_pk_bf16_f32 v161, v161, v174
	v_cvt_pk_bf16_f32 v162, v162, v173
	v_cvt_pk_bf16_f32 v163, v163, v172
	v_cvt_pk_bf16_f32 v164, v164, v171
	s_waitcnt lgkmcnt(0)
	v_mfma_f32_32x32x16_bf16 v[64:79], v[232:235], v[104:107], v[64:79]
	ds_read_b128 v[228:231], v205 offset:32768
	ds_read_b128 v[232:235], v205 offset:40960
	v_cvt_pk_bf16_f32 v165, v165, v170
	v_cvt_pk_bf16_f32 v166, v166, v169
	v_cvt_pk_bf16_f32 v167, v167, v168
	v_cvt_pk_bf16_f32 v168, v221, v222
	v_cvt_pk_bf16_f32 v169, v223, v224
	v_cvt_pk_bf16_f32 v170, v225, v214
	s_waitcnt lgkmcnt(1)
	v_mfma_f32_32x32x16_bf16 v[80:95], v[228:231], v[100:103], v[80:95]
	v_cvt_pk_bf16_f32 v171, v215, v216
	v_cvt_pk_bf16_f32 v172, v217, v218
	v_cvt_pk_bf16_f32 v173, v219, v220
	v_cvt_pk_bf16_f32 v174, v252, v226
	v_cvt_pk_bf16_f32 v175, v227, v253
	v_permlane32_swap_b32_e32 v212, v213
	s_waitcnt lgkmcnt(0)
	v_mfma_f32_32x32x16_bf16 v[64:79], v[232:235], v[100:103], v[64:79]
	ds_read_b128 v[228:231], v206 offset:32768
	ds_read_b128 v[232:235], v206 offset:40960
	v_permlane32_swap_b32_e32 v160, v162
	v_permlane32_swap_b32_e32 v161, v163
	v_permlane32_swap_b32_e32 v164, v166
	v_permlane32_swap_b32_e32 v165, v167
	v_permlane32_swap_b32_e32 v168, v170
	v_permlane32_swap_b32_e32 v169, v171
	s_waitcnt lgkmcnt(1)
	v_mfma_f32_32x32x16_bf16 v[80:95], v[228:231], v[96:99], v[80:95]
	v_permlane32_swap_b32_e32 v172, v174
	v_permlane32_swap_b32_e32 v173, v175
	s_waitcnt lgkmcnt(0)
	v_mfma_f32_32x32x16_bf16 v[64:79], v[232:235], v[96:99], v[64:79]
	s_cmpk_gt_u32 s61, 0x80
	s_cselect_b64 s[30:31], -1, 0
	s_and_b64 vcc, exec, s[30:31]
	s_cbranch_vccnz .LBB0_2129
	v_add_co_u32_e32 v132, vcc, 0xfffe8000, v184
	s_nop 1
	v_addc_co_u32_e32 v133, vcc, -1, v185, vcc
	global_load_dwordx4 v[128:131], v[132:133], off
	global_load_dwordx4 v[140:143], v[132:133], off offset:-512
	global_load_dwordx4 v[136:139], v[184:185], off
	s_nop 0
	global_load_dwordx4 v[132:135], v[184:185], off offset:-512
; #define SBAR() __builtin_amdgcn_sched_barrier(0)
; #define SWRITE(b, i) do { *(LAS bf16x8*)(V_lds + (b) * SHM_V + vst0) = sr_[i].vs0;          \
;     *(LAS bf16x8*)(V_lds + (b) * SHM_V + vst1) = sr_[i].vs1; const int kc = sc * 2;               \
;     *(LAS bf16x8*)(K_lds + (b) * SHM_K + KSWZ(sr, kc)) = sr_[i].ks0;                       \
;     *(LAS bf16x8*)(K_lds + (b) * SHM_K + KSWZ(32 + sr, kc)) = sr_[i].ks1; } while (0)
; #define SWAIT() asm volatile("s_waitcnt vmcnt(4)" ::: "memory")
; #define RESC(a) do { if (__any((a) < 1.f)) { if (hi == 0) al_l[r32] = (a); asm volatile("s_waitcnt lgkmcnt(0)" ::: "memory"); \
;     _Pragma("unroll") for (int d = 0; d < NDV; ++d) _Pragma("unroll") for (int r = 0; r < 16; ++r) o[d][r] *= al_l[crow(r, hi)]; } } while (0)
; template <int D0> __device__ __forceinline__ void pv_one(f32x16& od, int vb, bf16x8 pa0, bf16x8 pa1, bf16x8 pa2, bf16x8 pa3) {
;   const s16x4 l0 = tr_read<v_rd_off(D0, 0, 0)>(vb), h0 = tr_read<v_rd_off(D0, 0, 1)>(vb), l1 = tr_read<v_rd_off(D0, 1, 0)>(vb), h1 = tr_read<v_rd_off(D0, 1, 1)>(vb);
;   const s16x4 l2 = tr_read<v_rd_off(D0, 2, 0)>(vb), h2 = tr_read<v_rd_off(D0, 2, 1)>(vb), l3 = tr_read<v_rd_off(D0, 3, 0)>(vb), h3 = tr_read<v_rd_off(D0, 3, 1)>(vb);
;   asm volatile("s_waitcnt lgkmcnt(0)" ::: "memory"); SBAR();
;     ...
;   od = __builtin_amdgcn_mfma_f32_32x32x16_bf16(pa0, PK(l0, h0), od, 0, 0, 0);
;   od = __builtin_amdgcn_mfma_f32_32x32x16_bf16(pa1, PK(l1, h1), od, 0, 0, 0);
;   od = __builtin_amdgcn_mfma_f32_32x32x16_bf16(pa2, PK(l2, h2), od, 0, 0, 0);
;   od = __builtin_amdgcn_mfma_f32_32x32x16_bf16(pa3, PK(l3, h3), od, 0, 0, 0);
;     ...
; }
; template <int NDV>
; __device__ __forceinline__ void pv_d0(f32x16* o, int vb, bf16x8 pa0, bf16x8 pa1, bf16x8 pa2, bf16x8 pa3) {
;   pv_one<0>(o[0], vb, pa0, pa1, pa2, pa3); pv_one<1>(o[1], vb, pa0, pa1, pa2, pa3);
;   if constexpr (NDV == 4) { pv_one<2>(o[2], vb, pa0, pa1, pa2, pa3); pv_one<3>(o[3], vb, pa0, pa1, pa2, pa3); }
; }
; template <int NDQ, int NDV> ...
;     ...
;     pv_d0<NDV>(o, vb0 + SHM_V, pa0, pa1, pa2, pa3); partialSM(pA0, pA1, m_reg, mnA, alA, Cs, thr);
;     __syncthreads(); SWAIT(); SWRITE(1, SO);
;     RESC(alA); __syncthreads();
.LBB0_2129:
	ds_read_b64_tr_b16 v[214:215], v193 offset:0
	ds_read_b64_tr_b16 v[216:217], v193 offset:0x800
	ds_read_b64_tr_b16 v[218:219], v193 offset:0x1000
	ds_read_b64_tr_b16 v[220:221], v193 offset:0x1800
	ds_read_b64_tr_b16 v[222:223], v193 offset:0x2000
	ds_read_b64_tr_b16 v[224:225], v193 offset:0x2800
	ds_read_b64_tr_b16 v[226:227], v193 offset:0x3000
	ds_read_b64_tr_b16 v[228:229], v193 offset:0x3800
	s_waitcnt lgkmcnt(0)
	s_nop 0
	v_mfma_f32_32x32x16_bf16 v[0:15], v[160:163], v[214:217], v[0:15]
	ds_read_b64_tr_b16 v[214:215], v193 offset:0x200
	ds_read_b64_tr_b16 v[216:217], v193 offset:0xa00
	v_mfma_f32_32x32x16_bf16 v[0:15], v[164:167], v[218:221], v[0:15]
	ds_read_b64_tr_b16 v[218:219], v193 offset:0x1200
	ds_read_b64_tr_b16 v[220:221], v193 offset:0x1a00
	v_mfma_f32_32x32x16_bf16 v[0:15], v[168:171], v[222:225], v[0:15]
	ds_read_b64_tr_b16 v[222:223], v193 offset:0x2200
	ds_read_b64_tr_b16 v[224:225], v193 offset:0x2a00
	ds_read_b64_tr_b16 v[230:231], v193 offset:0x3200
	ds_read_b64_tr_b16 v[232:233], v193 offset:0x3a00
	s_waitcnt lgkmcnt(0)
	v_mfma_f32_32x32x16_bf16 v[0:15], v[172:175], v[226:229], v[0:15]
	v_mfma_f32_32x32x16_bf16 v[48:63], v[160:163], v[214:217], v[48:63]
	ds_read_b64_tr_b16 v[214:215], v193 offset:0x400
	ds_read_b64_tr_b16 v[216:217], v193 offset:0xc00
	v_mfma_f32_32x32x16_bf16 v[48:63], v[164:167], v[218:221], v[48:63]
	ds_read_b64_tr_b16 v[218:219], v193 offset:0x1400
	ds_read_b64_tr_b16 v[220:221], v193 offset:0x1c00
	v_mfma_f32_32x32x16_bf16 v[48:63], v[168:171], v[222:225], v[48:63]
	ds_read_b64_tr_b16 v[222:223], v193 offset:0x2400
	ds_read_b64_tr_b16 v[224:225], v193 offset:0x2c00
	ds_read_b64_tr_b16 v[226:227], v193 offset:0x3400
	ds_read_b64_tr_b16 v[228:229], v193 offset:0x3c00
	s_waitcnt lgkmcnt(0)
	v_mfma_f32_32x32x16_bf16 v[48:63], v[172:175], v[230:233], v[48:63]
	v_mfma_f32_32x32x16_bf16 v[32:47], v[160:163], v[214:217], v[32:47]
	ds_read_b64_tr_b16 v[214:215], v193 offset:0x600
	ds_read_b64_tr_b16 v[216:217], v193 offset:0xe00
	v_mfma_f32_32x32x16_bf16 v[32:47], v[164:167], v[218:221], v[32:47]
	ds_read_b64_tr_b16 v[218:219], v193 offset:0x1600
	ds_read_b64_tr_b16 v[220:221], v193 offset:0x1e00
	v_mfma_f32_32x32x16_bf16 v[32:47], v[168:171], v[222:225], v[32:47]
	ds_read_b64_tr_b16 v[222:223], v193 offset:0x2600
	ds_read_b64_tr_b16 v[224:225], v193 offset:0x2e00
	ds_read_b64_tr_b16 v[230:231], v193 offset:0x3600
	ds_read_b64_tr_b16 v[232:233], v193 offset:0x3e00
	s_waitcnt lgkmcnt(0)
	v_mfma_f32_32x32x16_bf16 v[32:47], v[172:175], v[226:229], v[32:47]
	v_mfma_f32_32x32x16_bf16 v[16:31], v[160:163], v[214:217], v[16:31]
	v_max_f32_e32 v226, v81, v81
	v_max_f32_e32 v227, v80, v80
	v_max_f32_e32 v226, v227, v226
	v_max3_f32 v226, v226, v82, v83
	v_max3_f32 v226, v226, v84, v85
	v_max3_f32 v160, v226, v86, v87
	v_max3_f32 v160, v160, v88, v89
	v_max3_f32 v160, v160, v90, v91
	v_mfma_f32_32x32x16_bf16 v[16:31], v[164:167], v[218:221], v[16:31]
	v_max3_f32 v160, v160, v92, v93
	v_max3_f32 v160, v160, v94, v95
	v_max3_f32 v160, v160, v64, v65
	v_max3_f32 v160, v160, v66, v67
	v_max3_f32 v160, v160, v68, v69
	v_max3_f32 v160, v160, v70, v71
	v_max3_f32 v160, v160, v72, v73
	v_max3_f32 v160, v160, v74, v75
	v_mfma_f32_32x32x16_bf16 v[16:31], v[168:171], v[222:225], v[16:31]
	v_max3_f32 v160, v160, v76, v77
	v_max3_f32 v160, v160, v78, v79
	v_mov_b32_e32 v161, v160
	s_nop 1
	v_permlane32_swap_b32_e32 v160, v161
	v_max_f32_e32 v161, v161, v161
	v_max_f32_e32 v160, v160, v160
	v_max_f32_e32 v160, v160, v161
	v_max_f32_e32 v162, v211, v211
	v_sub_f32_e32 v161, v160, v211
	v_max_f32_e32 v160, v162, v160
	v_mfma_f32_32x32x16_bf16 v[16:31], v[172:175], v[230:233], v[16:31]
	v_sub_f32_e32 v162, v211, v160
	v_mul_f32_e32 v162, 0x3e0293ee, v162
	v_exp_f32_e32 v162, v162
	v_cmp_ge_f32_e32 vcc, s48, v161
	s_cmp_eq_u64 vcc, exec
	s_cselect_b64 s[2:3], -1, 0
	s_barrier
	s_waitcnt vmcnt(4)
	s_cmp_lg_u64 s[30:31], 0
	s_cbranch_scc0 .Lgqa_nodrain
	s_waitcnt vmcnt(0)
.Lgqa_nodrain:
	v_cndmask_b32_e64 v161, v162, 1.0, s[2:3]
	v_cmp_gt_f32_e32 vcc, 1.0, v161
	ds_write_b128 v197, v[144:147] offset:16384
	ds_write_b128 v198, v[156:159] offset:16384
	ds_write_b128 v195, v[148:151] offset:49152
	ds_write_b128 v196, v[152:155] offset:49152
	s_cbranch_vccz .LBB0_2133
	s_and_saveexec_b64 s[36:37], s[0:1]
	ds_write_b32 v191, v161 offset:128
	s_or_b64 exec, exec, s[36:37]
	s_waitcnt lgkmcnt(0)
	v_add_u32_e32 v156, v183, v176
	ds_read_b128 v[144:147], v156 offset:224
	ds_read_b128 v[148:151], v156 offset:192
	ds_read_b128 v[152:155], v156 offset:160
	ds_read_b128 v[156:159], v156 offset:128
	s_waitcnt lgkmcnt(3)
	v_pk_mul_f32 v[12:13], v[12:13], v[144:145]
	s_waitcnt lgkmcnt(2)
	v_pk_mul_f32 v[8:9], v[8:9], v[148:149]
	s_waitcnt lgkmcnt(1)
	v_pk_mul_f32 v[4:5], v[4:5], v[152:153]
	v_pk_mul_f32 v[14:15], v[14:15], v[146:147]
	v_pk_mul_f32 v[10:11], v[10:11], v[150:151]
	v_pk_mul_f32 v[6:7], v[6:7], v[154:155]
	s_waitcnt lgkmcnt(0)
	v_pk_mul_f32 v[2:3], v[2:3], v[158:159]
	v_pk_mul_f32 v[0:1], v[0:1], v[156:157]
	v_pk_mul_f32 v[60:61], v[60:61], v[144:145]
	v_pk_mul_f32 v[56:57], v[56:57], v[148:149]
	v_pk_mul_f32 v[52:53], v[52:53], v[152:153]
	v_pk_mul_f32 v[62:63], v[62:63], v[146:147]
	v_pk_mul_f32 v[58:59], v[58:59], v[150:151]
	v_pk_mul_f32 v[54:55], v[54:55], v[154:155]
	v_pk_mul_f32 v[50:51], v[50:51], v[158:159]
	v_pk_mul_f32 v[48:49], v[48:49], v[156:157]
	v_pk_mul_f32 v[44:45], v[44:45], v[144:145]
	v_pk_mul_f32 v[40:41], v[40:41], v[148:149]
	v_pk_mul_f32 v[36:37], v[36:37], v[152:153]
	v_pk_mul_f32 v[46:47], v[46:47], v[146:147]
	v_pk_mul_f32 v[42:43], v[42:43], v[150:151]
	v_pk_mul_f32 v[38:39], v[38:39], v[154:155]
	v_pk_mul_f32 v[34:35], v[34:35], v[158:159]
	v_pk_mul_f32 v[32:33], v[32:33], v[156:157]
	v_pk_mul_f32 v[28:29], v[28:29], v[144:145]
	v_pk_mul_f32 v[24:25], v[24:25], v[148:149]
	v_pk_mul_f32 v[20:21], v[20:21], v[152:153]
	v_pk_mul_f32 v[30:31], v[30:31], v[146:147]
	v_pk_mul_f32 v[26:27], v[26:27], v[150:151]
	v_pk_mul_f32 v[22:23], v[22:23], v[154:155]
	v_pk_mul_f32 v[18:19], v[18:19], v[158:159]
	v_pk_mul_f32 v[16:17], v[16:17], v[156:157]
